# v26 + neighbourhood attention: running O / row-sum accumulators updated in place (68+68 v_mov phi copies per key-row step removed)
# speedup vs baseline: 1.0069x; 1.0040x over previous
; #define LAS __attribute__((address_space(3)))
; #define AT_WAIT_BAR(N) asm volatile("s_waitcnt vmcnt(" #N ") lgkmcnt(0)\n\ts_barrier" ::: "memory")
; DI void attn_even_lds(Frame& F, const float* rpb  , const float* gk  , const float* gq  ) {
;     ...
;         for (int s = 0; s < n; ++s) {
;             if (s + 2 < n) AT_WAIT_BAR(4); else if (s + 1 < n) AT_WAIT_BAR(2); else AT_WAIT_BAR(0);
;             if (s + 3 < n) AT_ISSUE(s + 3);
;             const LAS unsigned char* sk = F.lds + (s & 3) * AT_SLOT + bk; const LAS unsigned char* sv = F.lds + (s & 3) * AT_SLOT + bv;
.LBB0_299:
	s_cmp_ge_i32 s4, s46
	s_mov_b64 s[70:71], -1
	s_cbranch_scc0 .LBB0_306

; template <bool BIAS>
; DI void attn_head(f32x4 (&o)[4], float mref, float& ls, bf16x8 q0, bf16x8 q1, bf16x8 k00, bf16x8 k01, bf16x8 k10, bf16x8 k11,
;                   bf16x8 v0, bf16x8 v1, bf16x8 v2, bf16x8 v3, f32x4 b0, f32x4 b1, unsigned vm) {
;     const f32x4 z = {0.f, 0.f, 0.f, 0.f};
;     constexpr float C = 0.125f * LOG2E;
;     f32x4 s0 = MFMA16(k00, q0, z); s0 = MFMA16(k01, q1, s0);
;     f32x4 s1 = MFMA16(k10, q0, z); s1 = MFMA16(k11, q1, s1);
;     f32x4 p0, p1;
; #pragma unroll
;     for (int e = 0; e < 4; ++e) {
;         if (BIAS) { p0[e] = __builtin_amdgcn_exp2f(__builtin_fmaf(s0[e], C, b0[e] - mref)); p1[e] = __builtin_amdgcn_exp2f(__builtin_fmaf(s1[e], C, b1[e] - mref));
;                     if (!((vm >> e) & 1u)) p0[e] = 0.f; if (!((vm >> (4 + e)) & 1u)) p1[e] = 0.f; }
;         else { p0[e] = __builtin_amdgcn_exp2f(__builtin_fmaf(s0[e], C, -mref)); p1[e] = __builtin_amdgcn_exp2f(__builtin_fmaf(s1[e], C, -mref)); } }
;     ls += ((p0[0] + p0[1]) + (p0[2] + p0[3])) + ((p1[0] + p1[1]) + (p1[2] + p1[3]));
;     u32x4 pw; pw.x = pk2(p0[0], p0[1]); pw.y = pk2(p0[2], p0[3]); pw.z = pk2(p1[0], p1[1]); pw.w = pk2(p1[2], p1[3]);
; DI void attn_even_lds(Frame& F, const float* rpb  , const float* gk  , const float* gq  ) {
;     ...
;             if (s < nloc) {
;                 const int kr = rlo + s;
;                 if (kr >= r0 && kr < r0 + 8) {
;                     const LAS float* rp = bl + (kr - r + 7) * 31;
; #pragma unroll
;                     for (int j = 0; j < 4; ++j) {
;                         const int kc0 = j == 0 ? 0 : (j == 1 ? 8 : (j == 2 ? 24 : 32));
;                         const bf16x8 k00 = LDS_K(sk, kc0, 0, 0), k01 = LDS_K(sk, kc0, 0, 1), k10 = LDS_K(sk, kc0, 1, 0), k11 = LDS_K(sk, kc0, 1, 1);
;                         const bf16x8 v0 = LDS_V(sv, 0, kc0 >> 3), v1 = LDS_V(sv, 1, kc0 >> 3), v2 = LDS_V(sv, 2, kc0 >> 3), v3 = LDS_V(sv, 3, kc0 >> 3);
;                         f32x4 b0, b1; const u32x4 dt_ = dct[j * 64 + F.lane]; unsigned da_ = dt_.x, db_ = dt_.y;
; #pragma unroll
;                         for (int e = 0; e < 4; ++e) { b0[e] = rp[(da_ >> (8 * e)) & 255u]; b1[e] = rp[(db_ >> (8 * e)) & 255u]; }
;                         attn_head<true>(o[j], mx[j], ls[j], q[j][0], q[j][1], k00, k01, k10, k11, v0, v1, v2, v3, b0, b1, dt_.z);
;                         __builtin_amdgcn_sched_barrier(0);
;                     }
.LBB0_313:
	s_and_b32 s12, s4, 3
	s_mulk_i32 s12, 0x4800
	v_add_u32_e32 v220, s12, v214
	v_add_u32_e32 v219, v220, v207
	s_cmp_le_i32 s4, s88
	s_mov_b64 s[70:71], -1
	s_cbranch_scc0 .LBB0_317
	s_add_i32 s12, s87, s4
	s_cmp_ge_i32 s12, s37
	s_cselect_b64 s[30:31], -1, 0
	s_cmp_lt_i32 s12, s76
	s_cselect_b64 s[40:41], -1, 0
	s_and_b64 s[30:31], s[30:31], s[40:41]
	s_andn2_b64 vcc, exec, s[30:31]
	s_cbranch_vccnz .LBB0_316
	v_add_u32_e32 v178, v220, v206
	ds_read_b128 v[86:89], v178 offset:512
	ds_read_b128 v[94:97], v178 offset:2304
	ds_read_b128 v[102:105], v178 offset:2816
	ds_read_b128 v[110:113], v178
	ds_read_b128 v[114:117], v0
	v_add_u32_e32 v184, v219, v208
	s_waitcnt lgkmcnt(3)
	v_mfma_f32_16x16x32_bf16 v[94:97], v[94:97], v[2:5], 0
	v_add_u32_e32 v188, 0x2000, v184
	ds_read2_b64 v[118:121], v188 offset0:128 offset1:160
	s_waitcnt lgkmcnt(1)
	v_and_b32_e32 v117, 0xff, v114
	v_mfma_f32_16x16x32_bf16 v[110:113], v[110:113], v[2:5], 0
	v_and_b32_e32 v122, 0xff, v115
	v_bfe_u32 v123, v114, 8, 8
	v_bfe_u32 v125, v114, 16, 8
	v_mfma_f32_16x16x32_bf16 v[86:89], v[86:89], v[6:9], v[110:113]
	v_lshrrev_b32_e32 v114, 24, v114
	v_lshl_add_u32 v117, v117, 2, s36
	v_lshl_add_u32 v122, v122, 2, s36
	s_nop 0
	v_lshrrev_b32_e32 v111, 24, v115
	v_bfe_u32 v124, v115, 8, 8
	v_bfe_u32 v126, v115, 16, 8
	v_lshl_add_u32 v110, v114, 2, s36
	v_lshl_add_u32 v111, v111, 2, s36
	v_mfma_f32_16x16x32_bf16 v[94:97], v[102:105], v[6:9], v[94:97]
	v_lshl_add_u32 v123, v123, 2, s36
	v_lshl_add_u32 v124, v124, 2, s36
	v_lshl_add_u32 v125, v125, 2, s36
	v_lshl_add_u32 v126, v126, 2, s36
	ds_read_b32 v112, v117
	ds_read_b32 v113, v122
	ds_read_b32 v114, v123
	ds_read_b32 v115, v124
	ds_read_b32 v117, v125
	ds_read_b32 v122, v126
	ds_read_b32 v110, v110
	ds_read_b32 v111, v111
	s_waitcnt lgkmcnt(7)
	v_sub_f32_e32 v102, v112, v215
	v_fmac_f32_e32 v102, 0x3e38aa3b, v86
	v_exp_f32_e32 v86, v102
	s_waitcnt lgkmcnt(6)
	v_sub_f32_e32 v102, v113, v215
	v_fmac_f32_e32 v102, 0x3e38aa3b, v94
	v_exp_f32_e32 v94, v102
	v_bfe_i32 v102, v116, 0, 1
	v_and_b32_e32 v147, v102, v86
	v_bfe_i32 v86, v116, 4, 1
	v_and_b32_e32 v149, v86, v94
	s_waitcnt lgkmcnt(5)
	v_sub_f32_e32 v86, v114, v215
	v_fmac_f32_e32 v86, 0x3e38aa3b, v87
	s_waitcnt lgkmcnt(4)
	v_sub_f32_e32 v87, v115, v215
	v_exp_f32_e32 v86, v86
	v_fmac_f32_e32 v87, 0x3e38aa3b, v95
	v_exp_f32_e32 v87, v87
	v_bfe_i32 v94, v116, 1, 1
	v_and_b32_e32 v151, v94, v86
	v_bfe_i32 v86, v116, 5, 1
	v_and_b32_e32 v153, v86, v87
	s_waitcnt lgkmcnt(3)
	v_sub_f32_e32 v86, v117, v215
	v_fmac_f32_e32 v86, 0x3e38aa3b, v88
	s_waitcnt lgkmcnt(2)
	v_sub_f32_e32 v87, v122, v215
	v_exp_f32_e32 v86, v86
	v_fmac_f32_e32 v87, 0x3e38aa3b, v96
	v_exp_f32_e32 v87, v87
	v_bfe_i32 v88, v116, 2, 1
	v_and_b32_e32 v155, v88, v86
	v_bfe_i32 v86, v116, 6, 1
	v_and_b32_e32 v157, v86, v87
	s_waitcnt lgkmcnt(1)
	v_sub_f32_e32 v86, v110, v215
	v_fmac_f32_e32 v86, 0x3e38aa3b, v89
	v_exp_f32_e32 v86, v86
	v_add_u32_e32 v189, 0x2800, v184
	s_waitcnt lgkmcnt(0)
	v_sub_f32_e32 v87, v111, v215
	v_bfe_i32 v88, v116, 3, 1
	v_add_u32_e32 v142, 0x3000, v184
	v_add_u32_e32 v176, 0x3c00, v184
	v_fmac_f32_e32 v87, 0x3e38aa3b, v97
	v_and_b32_e32 v159, v88, v86
	v_bfe_i32 v86, v116, 7, 1
	ds_read2_b64 v[94:97], v189 offset0:160 offset1:192
	ds_read2_b64 v[102:105], v142 offset0:192 offset1:224
	ds_read2_b64 v[114:117], v176 offset0:96 offset1:128
	v_exp_f32_e32 v87, v87
	v_cvt_pk_bf16_f32 v110, v147, v151
	v_cvt_pk_bf16_f32 v111, v155, v159
	v_cvt_pk_bf16_f32 v112, v149, v153
	v_and_b32_e32 v161, v86, v87
	v_cvt_pk_bf16_f32 v113, v157, v161
	s_nop 1
	v_mfma_f32_16x16x32_bf16 v[106:109], v[118:121], v[110:113], v[106:109]
	s_waitcnt lgkmcnt(2)
	v_mfma_f32_16x16x32_bf16 v[98:101], v[94:97], v[110:113], v[98:101]
	s_waitcnt lgkmcnt(1)
	v_mfma_f32_16x16x32_bf16 v[90:93], v[102:105], v[110:113], v[90:93]
	s_waitcnt lgkmcnt(0)
	v_mfma_f32_16x16x32_bf16 v[82:85], v[114:117], v[110:113], v[82:85]
	ds_read_b128 v[114:117], v178 offset:1664
	ds_read_b128 v[118:121], v178 offset:3456
	ds_read_b128 v[122:125], v178 offset:1152
	ds_read_b128 v[126:129], v211
	ds_read_b128 v[130:133], v178 offset:3968
	ds_read2_b64 v[134:137], v188 offset0:144 offset1:176
	ds_read2_b64 v[138:141], v189 offset0:176 offset1:208
	ds_read2_b64 v[142:145], v142 offset0:208 offset1:240
	s_waitcnt lgkmcnt(5)
	v_mfma_f32_16x16x32_bf16 v[122:125], v[122:125], v[10:13], 0
	s_waitcnt lgkmcnt(4)
	v_and_b32_e32 v129, 0xff, v126
	v_bfe_u32 v148, v126, 8, 8
	v_bfe_u32 v152, v126, 16, 8
	v_mfma_f32_16x16x32_bf16 v[118:121], v[118:121], v[10:13], 0
	v_bfe_u32 v154, v127, 16, 8
	v_lshrrev_b32_e32 v126, 24, v126
	v_lshl_add_u32 v129, v129, 2, s36
	v_mfma_f32_16x16x32_bf16 v[114:117], v[114:117], v[14:17], v[122:125]
	v_and_b32_e32 v146, 0xff, v127
	v_bfe_u32 v150, v127, 8, 8
	v_lshl_add_u32 v154, v154, 2, s36
	v_lshrrev_b32_e32 v123, 24, v127
	v_lshl_add_u32 v122, v126, 2, s36
	v_lshl_add_u32 v123, v123, 2, s36
	v_lshl_add_u32 v146, v146, 2, s36
	v_lshl_add_u32 v148, v148, 2, s36
	v_lshl_add_u32 v150, v150, 2, s36
	v_lshl_add_u32 v152, v152, 2, s36
	ds_read_b32 v124, v129
	ds_read_b32 v125, v146
	ds_read_b32 v126, v148
	ds_read_b32 v127, v150
	ds_read_b32 v129, v152
	ds_read_b32 v154, v154
	ds_read_b32 v122, v122
	ds_read_b32 v123, v123
	s_waitcnt lgkmcnt(11)
	v_mfma_f32_16x16x32_bf16 v[118:121], v[130:133], v[14:17], v[118:121]
	s_waitcnt lgkmcnt(7)
	v_sub_f32_e32 v124, v124, v216
	v_fmac_f32_e32 v124, 0x3e38aa3b, v114
	v_exp_f32_e32 v114, v124
	s_waitcnt lgkmcnt(6)
	v_sub_f32_e32 v124, v125, v216
	ds_read2_b64 v[130:133], v176 offset0:112 offset1:144
	s_nop 0
	v_fmac_f32_e32 v124, 0x3e38aa3b, v118
	v_exp_f32_e32 v118, v124
	v_bfe_i32 v124, v128, 0, 1
	v_and_b32_e32 v146, v124, v114
	v_bfe_i32 v114, v128, 4, 1
	v_and_b32_e32 v148, v114, v118
	s_waitcnt lgkmcnt(6)
; #define LAS __attribute__((address_space(3)))
; template <bool BIAS>
; DI void attn_head(f32x4 (&o)[4], float mref, float& ls, bf16x8 q0, bf16x8 q1, bf16x8 k00, bf16x8 k01, bf16x8 k10, bf16x8 k11,
;                   bf16x8 v0, bf16x8 v1, bf16x8 v2, bf16x8 v3, f32x4 b0, f32x4 b1, unsigned vm) {
;     const f32x4 z = {0.f, 0.f, 0.f, 0.f};
;     constexpr float C = 0.125f * LOG2E;
;     f32x4 s0 = MFMA16(k00, q0, z); s0 = MFMA16(k01, q1, s0);
;     f32x4 s1 = MFMA16(k10, q0, z); s1 = MFMA16(k11, q1, s1);
;     f32x4 p0, p1;
; #pragma unroll
;     for (int e = 0; e < 4; ++e) {
;         if (BIAS) { p0[e] = __builtin_amdgcn_exp2f(__builtin_fmaf(s0[e], C, b0[e] - mref)); p1[e] = __builtin_amdgcn_exp2f(__builtin_fmaf(s1[e], C, b1[e] - mref));
;                     if (!((vm >> e) & 1u)) p0[e] = 0.f; if (!((vm >> (4 + e)) & 1u)) p1[e] = 0.f; }
;         else { p0[e] = __builtin_amdgcn_exp2f(__builtin_fmaf(s0[e], C, -mref)); p1[e] = __builtin_amdgcn_exp2f(__builtin_fmaf(s1[e], C, -mref)); } }
;     ls += ((p0[0] + p0[1]) + (p0[2] + p0[3])) + ((p1[0] + p1[1]) + (p1[2] + p1[3]));
;     u32x4 pw; pw.x = pk2(p0[0], p0[1]); pw.y = pk2(p0[2], p0[3]); pw.z = pk2(p1[0], p1[1]); pw.w = pk2(p1[2], p1[3]);
;     const bf16x8 pb = __builtin_bit_cast(bf16x8, pw);
; DI void attn_even_lds(Frame& F, const float* rpb  , const float* gk  , const float* gq  ) {
;     ...
;                     const LAS float* rp = bl + (kr - r + 7) * 31;
; #pragma unroll
;                     for (int j = 0; j < 4; ++j) {
;                         const int kc0 = j == 0 ? 0 : (j == 1 ? 8 : (j == 2 ? 24 : 32));
;                         const bf16x8 k00 = LDS_K(sk, kc0, 0, 0), k01 = LDS_K(sk, kc0, 0, 1), k10 = LDS_K(sk, kc0, 1, 0), k11 = LDS_K(sk, kc0, 1, 1);
;                         const bf16x8 v0 = LDS_V(sv, 0, kc0 >> 3), v1 = LDS_V(sv, 1, kc0 >> 3), v2 = LDS_V(sv, 2, kc0 >> 3), v3 = LDS_V(sv, 3, kc0 >> 3);
;                         f32x4 b0, b1; const u32x4 dt_ = dct[j * 64 + F.lane]; unsigned da_ = dt_.x, db_ = dt_.y;
; #pragma unroll
;                         for (int e = 0; e < 4; ++e) { b0[e] = rp[(da_ >> (8 * e)) & 255u]; b1[e] = rp[(db_ >> (8 * e)) & 255u]; }
;                         attn_head<true>(o[j], mx[j], ls[j], q[j][0], q[j][1], k00, k01, k10, k11, v0, v1, v2, v3, b0, b1, dt_.z);
;                         __builtin_amdgcn_sched_barrier(0);
;                     }
	v_sub_f32_e32 v114, v126, v216
	v_fmac_f32_e32 v114, 0x3e38aa3b, v115
	s_waitcnt lgkmcnt(5)
	v_sub_f32_e32 v115, v127, v216
	v_exp_f32_e32 v114, v114
	v_fmac_f32_e32 v115, 0x3e38aa3b, v119
	v_exp_f32_e32 v115, v115
	v_bfe_i32 v118, v128, 1, 1
	v_and_b32_e32 v150, v118, v114
	v_bfe_i32 v114, v128, 5, 1
	v_and_b32_e32 v152, v114, v115
	s_waitcnt lgkmcnt(4)
	v_sub_f32_e32 v114, v129, v216
	v_fmac_f32_e32 v114, 0x3e38aa3b, v116
	s_waitcnt lgkmcnt(3)
	v_sub_f32_e32 v115, v154, v216
	v_exp_f32_e32 v114, v114
	v_fmac_f32_e32 v115, 0x3e38aa3b, v120
	v_exp_f32_e32 v115, v115
	v_bfe_i32 v116, v128, 2, 1
	v_and_b32_e32 v154, v116, v114
	v_bfe_i32 v114, v128, 6, 1
	v_and_b32_e32 v156, v114, v115
	s_waitcnt lgkmcnt(2)
	v_sub_f32_e32 v114, v122, v216
	v_fmac_f32_e32 v114, 0x3e38aa3b, v117
	s_waitcnt lgkmcnt(1)
	v_sub_f32_e32 v115, v123, v216
	v_exp_f32_e32 v114, v114
	v_fmac_f32_e32 v115, 0x3e38aa3b, v121
	v_exp_f32_e32 v115, v115
	v_bfe_i32 v116, v128, 3, 1
	v_and_b32_e32 v158, v116, v114
	v_bfe_i32 v114, v128, 7, 1
	v_and_b32_e32 v160, v114, v115
	v_cvt_pk_bf16_f32 v126, v146, v150
	v_cvt_pk_bf16_f32 v127, v154, v158
	v_cvt_pk_bf16_f32 v128, v148, v152
	v_cvt_pk_bf16_f32 v129, v156, v160
	v_pk_add_f32 v[122:123], v[146:147], v[150:151]
	v_pk_add_f32 v[124:125], v[154:155], v[158:159]
	v_mfma_f32_16x16x32_bf16 v[78:81], v[134:137], v[126:129], v[78:81]
	v_add_f32_e64 v134, v122, v124
	v_add_f32_e64 v135, v123, v125
	v_pk_add_f32 v[136:137], v[148:149], v[152:153]
	v_mfma_f32_16x16x32_bf16 v[74:77], v[138:141], v[126:129], v[74:77]
	v_add_f32_e64 v138, v156, v160
	v_add_f32_e64 v139, v157, v161
	v_pk_add_f32 v[136:137], v[136:137], v[138:139]
	v_mfma_f32_16x16x32_bf16 v[70:73], v[142:145], v[126:129], v[70:73]
	v_add_f32_e64 v134, v134, v136
	v_add_f32_e64 v135, v135, v137
	v_pk_add_f32 v[174:175], v[174:175], v[134:135]
	s_waitcnt lgkmcnt(0)
	v_mfma_f32_16x16x32_bf16 v[66:69], v[130:133], v[126:129], v[66:69]
	ds_read_b128 v[130:133], v178 offset:3456
	ds_read_b128 v[134:137], v212
	ds_read_b128 v[138:141], v178 offset:3968
	ds_read_b128 v[142:145], v178 offset:5760
	ds_read_b128 v[146:149], v178 offset:6272
	ds_read2_b64 v[150:153], v188 offset0:176 offset1:208
	s_waitcnt lgkmcnt(5)
	v_mfma_f32_16x16x32_bf16 v[130:133], v[130:133], v[18:21], 0
	s_waitcnt lgkmcnt(4)
	v_and_b32_e32 v137, 0xff, v134
	v_and_b32_e32 v154, 0xff, v135
	v_bfe_u32 v155, v134, 8, 8
	s_waitcnt lgkmcnt(3)
	v_mfma_f32_16x16x32_bf16 v[130:133], v[138:141], v[22:25], v[130:133]
	v_bfe_u32 v156, v135, 8, 8
	v_bfe_u32 v157, v134, 16, 8
	v_bfe_u32 v158, v135, 16, 8
	s_waitcnt lgkmcnt(2)
	v_mfma_f32_16x16x32_bf16 v[138:141], v[142:145], v[18:21], 0
	v_lshrrev_b32_e32 v134, 24, v134
	v_lshrrev_b32_e32 v135, 24, v135
	v_lshl_add_u32 v137, v137, 2, s36
	v_lshl_add_u32 v154, v154, 2, s36
	v_lshl_add_u32 v134, v134, 2, s36
	v_lshl_add_u32 v135, v135, 2, s36
	v_lshl_add_u32 v155, v155, 2, s36
	v_lshl_add_u32 v156, v156, 2, s36
	v_lshl_add_u32 v157, v157, 2, s36
	v_lshl_add_u32 v158, v158, 2, s36
	ds_read_b32 v137, v137
	ds_read_b32 v142, v154
	ds_read_b32 v143, v155
	ds_read_b32 v144, v156
	ds_read_b32 v145, v157
	ds_read_b32 v154, v158
	ds_read_b32 v134, v134
	ds_read_b32 v135, v135
	s_waitcnt lgkmcnt(9)
	v_mfma_f32_16x16x32_bf16 v[138:141], v[146:149], v[22:25], v[138:141]
	s_waitcnt lgkmcnt(7)
	v_sub_f32_e32 v137, v137, v217
	v_fmac_f32_e32 v137, 0x3e38aa3b, v130
	v_exp_f32_e32 v130, v137
	s_waitcnt lgkmcnt(6)
	v_sub_f32_e32 v137, v142, v217
	v_add_u32_e32 v221, 0x4000, v184
	s_nop 0
	v_fmac_f32_e32 v137, 0x3e38aa3b, v138
	v_exp_f32_e32 v137, v137
	v_bfe_i32 v138, v136, 0, 1
	v_and_b32_e32 v179, v138, v130
	v_bfe_i32 v130, v136, 4, 1
	v_and_b32_e32 v185, v130, v137
	s_waitcnt lgkmcnt(5)
	v_sub_f32_e32 v130, v143, v217
	v_fmac_f32_e32 v130, 0x3e38aa3b, v131
	s_waitcnt lgkmcnt(4)
	v_sub_f32_e32 v131, v144, v217
	v_exp_f32_e32 v130, v130
	v_fmac_f32_e32 v131, 0x3e38aa3b, v139
	v_exp_f32_e32 v131, v131
	v_bfe_i32 v137, v136, 1, 1
	v_and_b32_e32 v235, v137, v130
	v_bfe_i32 v130, v136, 5, 1
	v_and_b32_e32 v237, v130, v131
	s_waitcnt lgkmcnt(3)
	v_sub_f32_e32 v130, v145, v217
	v_fmac_f32_e32 v130, 0x3e38aa3b, v132
	s_waitcnt lgkmcnt(2)
	v_sub_f32_e32 v131, v154, v217
	v_exp_f32_e32 v130, v130
	v_fmac_f32_e32 v131, 0x3e38aa3b, v140
	v_exp_f32_e32 v131, v131
	v_bfe_i32 v132, v136, 2, 1
	v_and_b32_e32 v239, v132, v130
	v_bfe_i32 v130, v136, 6, 1
	v_and_b32_e32 v241, v130, v131
	s_waitcnt lgkmcnt(1)
	v_sub_f32_e32 v130, v134, v217
	v_fmac_f32_e32 v130, 0x3e38aa3b, v133
	v_exp_f32_e32 v130, v130
	s_waitcnt lgkmcnt(0)
; #define LAS __attribute__((address_space(3)))
; template <bool BIAS>
; DI void attn_head(f32x4 (&o)[4], float mref, float& ls, bf16x8 q0, bf16x8 q1, bf16x8 k00, bf16x8 k01, bf16x8 k10, bf16x8 k11,
;                   bf16x8 v0, bf16x8 v1, bf16x8 v2, bf16x8 v3, f32x4 b0, f32x4 b1, unsigned vm) {
;     const f32x4 z = {0.f, 0.f, 0.f, 0.f};
;     constexpr float C = 0.125f * LOG2E;
;     f32x4 s0 = MFMA16(k00, q0, z); s0 = MFMA16(k01, q1, s0);
;     f32x4 s1 = MFMA16(k10, q0, z); s1 = MFMA16(k11, q1, s1);
;     f32x4 p0, p1;
; #pragma unroll
;     for (int e = 0; e < 4; ++e) {
;         if (BIAS) { p0[e] = __builtin_amdgcn_exp2f(__builtin_fmaf(s0[e], C, b0[e] - mref)); p1[e] = __builtin_amdgcn_exp2f(__builtin_fmaf(s1[e], C, b1[e] - mref));
;                     if (!((vm >> e) & 1u)) p0[e] = 0.f; if (!((vm >> (4 + e)) & 1u)) p1[e] = 0.f; }
;         else { p0[e] = __builtin_amdgcn_exp2f(__builtin_fmaf(s0[e], C, -mref)); p1[e] = __builtin_amdgcn_exp2f(__builtin_fmaf(s1[e], C, -mref)); } }
;     ls += ((p0[0] + p0[1]) + (p0[2] + p0[3])) + ((p1[0] + p1[1]) + (p1[2] + p1[3]));
;     u32x4 pw; pw.x = pk2(p0[0], p0[1]); pw.y = pk2(p0[2], p0[3]); pw.z = pk2(p1[0], p1[1]); pw.w = pk2(p1[2], p1[3]);
;     const bf16x8 pb = __builtin_bit_cast(bf16x8, pw);
; DI void attn_even_lds(Frame& F, const float* rpb  , const float* gk  , const float* gq  ) {
;     ...
;                     const LAS float* rp = bl + (kr - r + 7) * 31;
; #pragma unroll
;                     for (int j = 0; j < 4; ++j) {
;                         const int kc0 = j == 0 ? 0 : (j == 1 ? 8 : (j == 2 ? 24 : 32));
;                         const bf16x8 k00 = LDS_K(sk, kc0, 0, 0), k01 = LDS_K(sk, kc0, 0, 1), k10 = LDS_K(sk, kc0, 1, 0), k11 = LDS_K(sk, kc0, 1, 1);
;                         const bf16x8 v0 = LDS_V(sv, 0, kc0 >> 3), v1 = LDS_V(sv, 1, kc0 >> 3), v2 = LDS_V(sv, 2, kc0 >> 3), v3 = LDS_V(sv, 3, kc0 >> 3);
;                         f32x4 b0, b1; const u32x4 dt_ = dct[j * 64 + F.lane]; unsigned da_ = dt_.x, db_ = dt_.y;
; #pragma unroll
;                         for (int e = 0; e < 4; ++e) { b0[e] = rp[(da_ >> (8 * e)) & 255u]; b1[e] = rp[(db_ >> (8 * e)) & 255u]; }
;                         attn_head<true>(o[j], mx[j], ls[j], q[j][0], q[j][1], k00, k01, k10, k11, v0, v1, v2, v3, b0, b1, dt_.z);
;                         __builtin_amdgcn_sched_barrier(0);
;                     }
	v_sub_f32_e32 v131, v135, v217
	v_bfe_i32 v132, v136, 3, 1
	v_add_u32_e32 v138, 0x3400, v184
	v_fmac_f32_e32 v131, 0x3e38aa3b, v141
	v_and_b32_e32 v243, v132, v130
	v_bfe_i32 v130, v136, 7, 1
	ds_read2_b64 v[134:137], v189 offset0:208 offset1:240
	ds_read2_b64 v[138:141], v138 offset0:112 offset1:144
	ds_read2_b64 v[146:149], v221 offset0:16 offset1:48
	v_exp_f32_e32 v131, v131
	v_cvt_pk_bf16_f32 v142, v179, v235
	v_cvt_pk_bf16_f32 v143, v239, v243
	v_cvt_pk_bf16_f32 v144, v185, v237
	v_and_b32_e32 v245, v130, v131
	v_cvt_pk_bf16_f32 v145, v241, v245
	s_nop 1
	v_mfma_f32_16x16x32_bf16 v[62:65], v[150:153], v[142:145], v[62:65]
	s_waitcnt lgkmcnt(2)
	v_mfma_f32_16x16x32_bf16 v[58:61], v[134:137], v[142:145], v[58:61]
	s_waitcnt lgkmcnt(1)
	v_mfma_f32_16x16x32_bf16 v[54:57], v[138:141], v[142:145], v[54:57]
	s_waitcnt lgkmcnt(0)
	v_mfma_f32_16x16x32_bf16 v[50:53], v[146:149], v[142:145], v[50:53]
	ds_read_b128 v[146:149], v178 offset:5120
	ds_read_b128 v[150:153], v178 offset:6912
	ds_read_b128 v[154:157], v178 offset:7424
	ds_read2_b64 v[158:161], v188 offset0:192 offset1:224
	ds_read_b128 v[188:191], v178 offset:4608
	ds_read_b128 v[222:225], v213
	s_waitcnt lgkmcnt(4)
	v_mfma_f32_16x16x32_bf16 v[150:153], v[150:153], v[26:29], 0
	v_add_u32_e32 v178, 0x2c00, v184
	ds_read2_b64 v[226:229], v178 offset0:96 offset1:128
	v_add_u32_e32 v178, 0x3800, v184
	s_waitcnt lgkmcnt(2)
	v_mfma_f32_16x16x32_bf16 v[188:191], v[188:191], v[26:29], 0
	ds_read2_b64 v[230:233], v178 offset1:32
	s_waitcnt lgkmcnt(2)
	v_and_b32_e32 v178, 0xff, v222
	v_and_b32_e32 v184, 0xff, v223
	v_mfma_f32_16x16x32_bf16 v[146:149], v[146:149], v[30:33], v[188:191]
	v_bfe_u32 v225, v222, 8, 8
	v_bfe_u32 v236, v222, 16, 8
	v_lshrrev_b32_e32 v222, 24, v222
	v_lshrrev_b32_e32 v189, 24, v223
	v_lshl_add_u32 v178, v178, 2, s36
	v_lshl_add_u32 v184, v184, 2, s36
	v_bfe_u32 v234, v223, 8, 8
	v_bfe_u32 v238, v223, 16, 8
	v_lshl_add_u32 v188, v222, 2, s36
	v_lshl_add_u32 v189, v189, 2, s36
	v_mfma_f32_16x16x32_bf16 v[150:153], v[154:157], v[30:33], v[150:153]
	v_lshl_add_u32 v225, v225, 2, s36
	v_lshl_add_u32 v234, v234, 2, s36
	v_lshl_add_u32 v236, v236, 2, s36
	v_lshl_add_u32 v238, v238, 2, s36
	ds_read_b32 v178, v178
	ds_read_b32 v184, v184
	ds_read_b32 v190, v225
	ds_read_b32 v191, v234
	ds_read_b32 v222, v236
	ds_read_b32 v223, v238
	ds_read_b32 v188, v188
	ds_read_b32 v189, v189
	s_waitcnt lgkmcnt(7)
	v_sub_f32_e32 v154, v178, v218
	v_fmac_f32_e32 v154, 0x3e38aa3b, v146
	v_exp_f32_e32 v146, v154
	s_waitcnt lgkmcnt(6)
	v_sub_f32_e32 v154, v184, v218
	v_fmac_f32_e32 v154, 0x3e38aa3b, v150
	v_exp_f32_e32 v150, v154
	v_bfe_i32 v154, v224, 0, 1
	v_and_b32_e32 v178, v154, v146
	v_bfe_i32 v146, v224, 4, 1
	v_and_b32_e32 v184, v146, v150
	s_waitcnt lgkmcnt(5)
	v_sub_f32_e32 v146, v190, v218
	v_fmac_f32_e32 v146, 0x3e38aa3b, v147
	s_waitcnt lgkmcnt(4)
	v_sub_f32_e32 v147, v191, v218
	v_exp_f32_e32 v146, v146
	v_fmac_f32_e32 v147, 0x3e38aa3b, v151
	v_exp_f32_e32 v147, v147
	v_bfe_i32 v150, v224, 1, 1
	v_and_b32_e32 v234, v150, v146
	v_bfe_i32 v146, v224, 5, 1
	v_and_b32_e32 v236, v146, v147
	s_waitcnt lgkmcnt(3)
	v_sub_f32_e32 v146, v222, v218
	v_fmac_f32_e32 v146, 0x3e38aa3b, v148
	s_waitcnt lgkmcnt(2)
	v_sub_f32_e32 v147, v223, v218
	v_exp_f32_e32 v146, v146
	v_fmac_f32_e32 v147, 0x3e38aa3b, v152
	v_exp_f32_e32 v147, v147
	v_bfe_i32 v148, v224, 2, 1
	v_and_b32_e32 v238, v148, v146
	v_bfe_i32 v146, v224, 6, 1
	v_and_b32_e32 v240, v146, v147
	s_waitcnt lgkmcnt(1)
	v_sub_f32_e32 v146, v188, v218
	v_fmac_f32_e32 v146, 0x3e38aa3b, v149
	s_waitcnt lgkmcnt(0)
	v_sub_f32_e32 v147, v189, v218
	v_exp_f32_e32 v146, v146
	v_fmac_f32_e32 v147, 0x3e38aa3b, v153
	v_exp_f32_e32 v147, v147
	v_bfe_i32 v148, v224, 3, 1
	v_and_b32_e32 v242, v148, v146
	v_bfe_i32 v146, v224, 7, 1
	v_and_b32_e32 v244, v146, v147
	v_cvt_pk_bf16_f32 v188, v178, v234
	v_cvt_pk_bf16_f32 v189, v238, v242
	v_cvt_pk_bf16_f32 v190, v184, v236
	v_cvt_pk_bf16_f32 v191, v240, v244
	v_pk_add_f32 v[154:155], v[178:179], v[234:235]
	v_pk_add_f32 v[156:157], v[238:239], v[242:243]
	v_mfma_f32_16x16x32_bf16 v[46:49], v[158:161], v[188:191], v[46:49]
	ds_read2_b64 v[158:161], v221 offset0:32 offset1:64
	v_pk_add_f32 v[178:179], v[154:155], v[156:157]
	v_pk_add_f32 v[184:185], v[184:185], v[236:237]
	v_mfma_f32_16x16x32_bf16 v[42:45], v[226:229], v[188:191], v[42:45]
	v_add_f32_e64 v222, v240, v244
	v_add_f32_e64 v223, v241, v245
	v_pk_add_f32 v[184:185], v[184:185], v[222:223]
	v_mfma_f32_16x16x32_bf16 v[38:41], v[230:233], v[188:191], v[38:41]
	v_add_f32_e64 v178, v178, v184
	v_add_f32_e64 v179, v179, v185
	v_pk_add_f32 v[172:173], v[172:173], v[178:179]
	s_waitcnt lgkmcnt(0)
	v_mfma_f32_16x16x32_bf16 v[34:37], v[158:161], v[188:191], v[34:37]

; DI unsigned pk2(float lo, float hi) { f32x2 v = {lo, hi}; bf16x2_t b = __builtin_convertvector(v, bf16x2_t); return __builtin_bit_cast(unsigned, b); }
; #define MFMA16(a, b, c) __builtin_amdgcn_mfma_f32_16x16x32_bf16((a), (b), (c), 0, 0, 0)
; DI void attn_group4(f32x4 (&o)[4][4], const float (&mref)[4], float (&ls)[4], const bf16x8 (&q)[4][2], bf16x8 k00, bf16x8 k01, bf16x8 k10, bf16x8 k11,
;                     bf16x8 v0, bf16x8 v1, bf16x8 v2, bf16x8 v3) {
;     const f32x4 z = {0.f, 0.f, 0.f, 0.f};
;     constexpr float C = 0.125f * LOG2E;
;     f32x4 s0[4], s1[4];
;     __builtin_amdgcn_s_setprio(1);
; #pragma unroll
;     for (int h = 0; h < 4; ++h) { s0[h] = MFMA16(k00, q[h][0], z); s1[h] = MFMA16(k10, q[h][0], z); }
; #pragma unroll
;     for (int h = 0; h < 4; ++h) { s0[h] = MFMA16(k01, q[h][1], s0[h]); s1[h] = MFMA16(k11, q[h][1], s1[h]); }
;     __builtin_amdgcn_s_setprio(0);
;     bf16x8 pb[4];
; #pragma unroll
;     for (int h = 0; h < 4; ++h) {
;         f32x4 p0, p1;
; #pragma unroll
;         for (int e = 0; e < 4; ++e) { p0[e] = __builtin_amdgcn_exp2f(__builtin_fmaf(s0[h][e], C, -mref[h])); p1[e] = __builtin_amdgcn_exp2f(__builtin_fmaf(s1[h][e], C, -mref[h])); }
;         ls[h] += ((p0[0] + p0[1]) + (p0[2] + p0[3])) + ((p1[0] + p1[1]) + (p1[2] + p1[3]));
;         u32x4 pw; pw.x = pk2(p0[0], p0[1]); pw.y = pk2(p0[2], p0[3]); pw.z = pk2(p1[0], p1[1]); pw.w = pk2(p1[2], p1[3]);
;         pb[h] = __builtin_bit_cast(bf16x8, pw);
;     }
;     __builtin_amdgcn_s_setprio(1);
; #pragma unroll
;     for (int h = 0; h < 4; ++h) { o[h][0] = MFMA16(v0, pb[h], o[h][0]); o[h][1] = MFMA16(v1, pb[h], o[h][1]); o[h][2] = MFMA16(v2, pb[h], o[h][2]); o[h][3] = MFMA16(v3, pb[h], o[h][3]); }
;     __builtin_amdgcn_s_setprio(0);
; }
; DI void attn_even_lds(Frame& F, const float* rpb  , const float* gk  , const float* gq  ) {
;     ...
;                 for (int hf = 0; hf < 2; ++hf) {
;                     const bf16x8 k00 = LDS_K(sk, hf * 32, 0, 0), k01 = LDS_K(sk, hf * 32, 0, 1), k10 = LDS_K(sk, hf * 32, 1, 0), k11 = LDS_K(sk, hf * 32, 1, 1);
;                     const bf16x8 v0 = LDS_V(sv, 0, hf * 4), v1 = LDS_V(sv, 1, hf * 4), v2 = LDS_V(sv, 2, hf * 4), v3 = LDS_V(sv, 3, hf * 4);
;                     attn_group4(o, mx, ls, q, k00, k01, k10, k11, v0, v1, v2, v3);
;                     __builtin_amdgcn_sched_barrier(0);
;                 }
.LBB0_317:
	s_andn2_b64 vcc, exec, s[70:71]
	s_cbranch_vccnz .LBB0_319
	s_nop 4
	v_add_u32_e32 v158, v219, v208
	v_add_u32_e32 v156, v220, v206
	v_add_u32_e32 v114, 0x2800, v158
	ds_read_b128 v[86:89], v156
	ds_read_b128 v[94:97], v156 offset:512
	ds_read_b128 v[102:105], v156 offset:2304
	ds_read_b128 v[110:113], v156 offset:2816
	ds_read2_b64 v[124:127], v114 offset0:160 offset1:192
	v_add_u32_e32 v114, 0x3000, v158
	v_add_u32_e32 v157, 0x2000, v158
	ds_read2_b64 v[128:131], v114 offset0:192 offset1:224
	v_add_u32_e32 v114, 0x3c00, v158
	ds_read2_b64 v[120:123], v157 offset0:128 offset1:160
	ds_read2_b64 v[132:135], v114 offset0:96 offset1:128
	s_setprio 1
	s_waitcnt lgkmcnt(7)
	v_mfma_f32_16x16x32_bf16 v[114:117], v[86:89], v[2:5], 0
	s_waitcnt lgkmcnt(5)
	v_mfma_f32_16x16x32_bf16 v[136:139], v[102:105], v[2:5], 0
	v_mfma_f32_16x16x32_bf16 v[140:143], v[86:89], v[10:13], 0
	v_mfma_f32_16x16x32_bf16 v[144:147], v[102:105], v[10:13], 0
	v_mfma_f32_16x16x32_bf16 v[148:151], v[86:89], v[18:21], 0
	v_mfma_f32_16x16x32_bf16 v[152:155], v[102:105], v[18:21], 0
	v_mfma_f32_16x16x32_bf16 v[86:89], v[86:89], v[26:29], 0
	v_mfma_f32_16x16x32_bf16 v[102:105], v[102:105], v[26:29], 0
	v_mfma_f32_16x16x32_bf16 v[114:117], v[94:97], v[6:9], v[114:117]
	s_waitcnt lgkmcnt(4)
	v_mfma_f32_16x16x32_bf16 v[136:139], v[110:113], v[6:9], v[136:139]
	v_mfma_f32_16x16x32_bf16 v[140:143], v[94:97], v[14:17], v[140:143]
	v_mfma_f32_16x16x32_bf16 v[144:147], v[110:113], v[14:17], v[144:147]
	v_mfma_f32_16x16x32_bf16 v[148:151], v[94:97], v[22:25], v[148:151]
	v_mfma_f32_16x16x32_bf16 v[152:155], v[110:113], v[22:25], v[152:155]
	v_mfma_f32_16x16x32_bf16 v[86:89], v[94:97], v[30:33], v[86:89]
	v_mfma_f32_16x16x32_bf16 v[94:97], v[110:113], v[30:33], v[102:105]
	s_setprio 0
	s_nop 1
	v_fma_f32 v102, v114, s96, -v215
	v_exp_f32_e32 v185, v102
	v_fma_f32 v102, v136, s96, -v215
	v_exp_f32_e32 v225, v102
	v_fma_f32 v102, v115, s96, -v215
	v_exp_f32_e32 v227, v102
	v_fma_f32 v102, v137, s96, -v215
	v_exp_f32_e32 v229, v102
	v_fma_f32 v102, v116, s96, -v215
	v_exp_f32_e32 v231, v102
	v_fma_f32 v102, v138, s96, -v215
	v_exp_f32_e32 v233, v102
	v_fma_f32 v102, v117, s96, -v215
	v_exp_f32_e32 v235, v102
	v_fma_f32 v102, v139, s96, -v215
	v_exp_f32_e32 v237, v102
	v_fma_f32 v102, v140, s96, -v216
	v_exp_f32_e32 v184, v102
	v_fma_f32 v102, v144, s96, -v216
	v_exp_f32_e32 v224, v102
	v_fma_f32 v102, v141, s96, -v216
	v_exp_f32_e32 v226, v102
	v_fma_f32 v102, v145, s96, -v216
	v_exp_f32_e32 v228, v102
	v_fma_f32 v102, v142, s96, -v216
	v_exp_f32_e32 v230, v102
	v_fma_f32 v102, v146, s96, -v216
	v_exp_f32_e32 v232, v102
	v_fma_f32 v102, v143, s96, -v216
	v_exp_f32_e32 v234, v102
	v_fma_f32 v102, v147, s96, -v216
	v_exp_f32_e32 v236, v102
	v_fma_f32 v102, v148, s96, -v217
	v_exp_f32_e32 v115, v102
	v_fma_f32 v102, v152, s96, -v217
	v_exp_f32_e32 v103, v102
	v_fma_f32 v102, v149, s96, -v217
	v_exp_f32_e32 v119, v102
	v_fma_f32 v102, v153, s96, -v217
	v_exp_f32_e32 v111, v102
	v_fma_f32 v102, v150, s96, -v217
	v_exp_f32_e32 v117, v102
	v_fma_f32 v102, v154, s96, -v217
	v_exp_f32_e32 v105, v102
	v_fma_f32 v102, v151, s96, -v217
	v_fma_f32 v86, v86, s96, -v218
	v_exp_f32_e32 v239, v102
	v_fma_f32 v102, v155, s96, -v217
	v_exp_f32_e32 v114, v86
	v_fma_f32 v86, v94, s96, -v218
	v_exp_f32_e32 v113, v102
	v_exp_f32_e32 v102, v86
	v_fma_f32 v86, v87, s96, -v218
	v_exp_f32_e32 v118, v86
	v_fma_f32 v86, v95, s96, -v218
	v_exp_f32_e32 v110, v86
	v_fma_f32 v86, v88, s96, -v218
	v_exp_f32_e32 v116, v86
	v_fma_f32 v86, v96, s96, -v218
	v_exp_f32_e32 v104, v86
	v_fma_f32 v86, v89, s96, -v218
	v_exp_f32_e32 v238, v86
	v_fma_f32 v86, v97, s96, -v218
	v_exp_f32_e32 v112, v86
	v_cvt_pk_bf16_f32 v136, v185, v227
	v_cvt_pk_bf16_f32 v137, v231, v235
	v_cvt_pk_bf16_f32 v138, v225, v229
	v_cvt_pk_bf16_f32 v139, v233, v237
	v_cvt_pk_bf16_f32 v140, v184, v226
	v_cvt_pk_bf16_f32 v141, v230, v234
	v_cvt_pk_bf16_f32 v142, v224, v228
	v_cvt_pk_bf16_f32 v143, v232, v236
	v_cvt_pk_bf16_f32 v144, v115, v119
	v_cvt_pk_bf16_f32 v145, v117, v239
	v_cvt_pk_bf16_f32 v146, v103, v111
	v_cvt_pk_bf16_f32 v147, v105, v113
	v_cvt_pk_bf16_f32 v148, v114, v118
	v_cvt_pk_bf16_f32 v149, v116, v238
	v_cvt_pk_bf16_f32 v150, v102, v110
	v_cvt_pk_bf16_f32 v151, v104, v112
	s_setprio 1
	s_waitcnt lgkmcnt(1)
	v_mfma_f32_16x16x32_bf16 v[86:89], v[120:123], v[136:139], v[106:109]
	v_mfma_f32_16x16x32_bf16 v[94:97], v[124:127], v[136:139], v[98:101]
	v_mfma_f32_16x16x32_bf16 v[90:93], v[128:131], v[136:139], v[90:93]
	s_waitcnt lgkmcnt(0)
	v_mfma_f32_16x16x32_bf16 v[82:85], v[132:135], v[136:139], v[82:85]
	v_mfma_f32_16x16x32_bf16 v[78:81], v[120:123], v[140:143], v[78:81]
	v_mfma_f32_16x16x32_bf16 v[74:77], v[124:127], v[140:143], v[74:77]
	v_mfma_f32_16x16x32_bf16 v[70:73], v[128:131], v[140:143], v[70:73]
	v_mfma_f32_16x16x32_bf16 v[66:69], v[132:135], v[140:143], v[66:69]
	v_mfma_f32_16x16x32_bf16 v[62:65], v[120:123], v[144:147], v[62:65]
	v_mfma_f32_16x16x32_bf16 v[58:61], v[124:127], v[144:147], v[58:61]
	v_mfma_f32_16x16x32_bf16 v[54:57], v[128:131], v[144:147], v[54:57]
	v_mfma_f32_16x16x32_bf16 v[50:53], v[132:135], v[144:147], v[50:53]
	v_mfma_f32_16x16x32_bf16 v[46:49], v[120:123], v[148:151], v[46:49]
	v_mfma_f32_16x16x32_bf16 v[42:45], v[124:127], v[148:151], v[42:45]
	v_mfma_f32_16x16x32_bf16 v[38:41], v[128:131], v[148:151], v[38:41]
	v_mfma_f32_16x16x32_bf16 v[34:37], v[132:135], v[148:151], v[34:37]
	s_setprio 0
	ds_read_b128 v[106:109], v156 offset:4608
	ds_read_b128 v[120:123], v156 offset:5120
	ds_read_b128 v[124:127], v156 offset:6912
	ds_read_b128 v[128:131], v156 offset:7424
	ds_read2_b64 v[98:101], v157 offset0:192 offset1:224
	v_add_u32_e32 v132, 0x2c00, v158
	ds_read2_b64 v[150:153], v132 offset0:96 offset1:128
	v_add_u32_e32 v132, 0x3800, v158
	ds_read2_b64 v[154:157], v132 offset1:32
	v_add_u32_e32 v132, 0x4000, v158
	ds_read2_b64 v[158:161], v132 offset0:32 offset1:64
	s_setprio 1
	s_waitcnt lgkmcnt(7)
; DI unsigned pk2(float lo, float hi) { f32x2 v = {lo, hi}; bf16x2_t b = __builtin_convertvector(v, bf16x2_t); return __builtin_bit_cast(unsigned, b); }
; #define MFMA16(a, b, c) __builtin_amdgcn_mfma_f32_16x16x32_bf16((a), (b), (c), 0, 0, 0)
; DI void attn_group4(f32x4 (&o)[4][4], const float (&mref)[4], float (&ls)[4], const bf16x8 (&q)[4][2], bf16x8 k00, bf16x8 k01, bf16x8 k10, bf16x8 k11,
;                     bf16x8 v0, bf16x8 v1, bf16x8 v2, bf16x8 v3) {
;     const f32x4 z = {0.f, 0.f, 0.f, 0.f};
;     constexpr float C = 0.125f * LOG2E;
;     f32x4 s0[4], s1[4];
;     __builtin_amdgcn_s_setprio(1);
; #pragma unroll
;     for (int h = 0; h < 4; ++h) { s0[h] = MFMA16(k00, q[h][0], z); s1[h] = MFMA16(k10, q[h][0], z); }
; #pragma unroll
;     for (int h = 0; h < 4; ++h) { s0[h] = MFMA16(k01, q[h][1], s0[h]); s1[h] = MFMA16(k11, q[h][1], s1[h]); }
;     __builtin_amdgcn_s_setprio(0);
;     bf16x8 pb[4];
; #pragma unroll
;     for (int h = 0; h < 4; ++h) {
;         f32x4 p0, p1;
; #pragma unroll
;         for (int e = 0; e < 4; ++e) { p0[e] = __builtin_amdgcn_exp2f(__builtin_fmaf(s0[h][e], C, -mref[h])); p1[e] = __builtin_amdgcn_exp2f(__builtin_fmaf(s1[h][e], C, -mref[h])); }
;         ls[h] += ((p0[0] + p0[1]) + (p0[2] + p0[3])) + ((p1[0] + p1[1]) + (p1[2] + p1[3]));
;         u32x4 pw; pw.x = pk2(p0[0], p0[1]); pw.y = pk2(p0[2], p0[3]); pw.z = pk2(p1[0], p1[1]); pw.w = pk2(p1[2], p1[3]);
;         pb[h] = __builtin_bit_cast(bf16x8, pw);
;     }
;     __builtin_amdgcn_s_setprio(1);
; #pragma unroll
;     for (int h = 0; h < 4; ++h) { o[h][0] = MFMA16(v0, pb[h], o[h][0]); o[h][1] = MFMA16(v1, pb[h], o[h][1]); o[h][2] = MFMA16(v2, pb[h], o[h][2]); o[h][3] = MFMA16(v3, pb[h], o[h][3]); }
;     __builtin_amdgcn_s_setprio(0);
; }
; DI void attn_even_lds(Frame& F, const float* rpb  , const float* gk  , const float* gq  ) {
;     ...
;                 for (int hf = 0; hf < 2; ++hf) {
;                     const bf16x8 k00 = LDS_K(sk, hf * 32, 0, 0), k01 = LDS_K(sk, hf * 32, 0, 1), k10 = LDS_K(sk, hf * 32, 1, 0), k11 = LDS_K(sk, hf * 32, 1, 1);
;                     const bf16x8 v0 = LDS_V(sv, 0, hf * 4), v1 = LDS_V(sv, 1, hf * 4), v2 = LDS_V(sv, 2, hf * 4), v3 = LDS_V(sv, 3, hf * 4);
;                     attn_group4(o, mx, ls, q, k00, k01, k10, k11, v0, v1, v2, v3);
;                     __builtin_amdgcn_sched_barrier(0);
;                 }
	v_mfma_f32_16x16x32_bf16 v[132:135], v[106:109], v[2:5], 0
	s_waitcnt lgkmcnt(5)
	v_mfma_f32_16x16x32_bf16 v[136:139], v[124:127], v[2:5], 0
	v_mfma_f32_16x16x32_bf16 v[140:143], v[106:109], v[10:13], 0
	v_mfma_f32_16x16x32_bf16 v[144:147], v[124:127], v[10:13], 0
	v_mfma_f32_16x16x32_bf16 v[176:179], v[106:109], v[18:21], 0
	v_mfma_f32_16x16x32_bf16 v[188:191], v[124:127], v[18:21], 0
	v_mfma_f32_16x16x32_bf16 v[106:109], v[106:109], v[26:29], 0
	v_mfma_f32_16x16x32_bf16 v[124:127], v[124:127], v[26:29], 0
	v_mfma_f32_16x16x32_bf16 v[132:135], v[120:123], v[6:9], v[132:135]
	s_waitcnt lgkmcnt(4)
	v_mfma_f32_16x16x32_bf16 v[136:139], v[128:131], v[6:9], v[136:139]
	v_mfma_f32_16x16x32_bf16 v[140:143], v[120:123], v[14:17], v[140:143]
	v_mfma_f32_16x16x32_bf16 v[144:147], v[128:131], v[14:17], v[144:147]
	v_mfma_f32_16x16x32_bf16 v[220:223], v[120:123], v[22:25], v[176:179]
	v_mfma_f32_16x16x32_bf16 v[106:109], v[120:123], v[30:33], v[106:109]
	v_mfma_f32_16x16x32_bf16 v[120:123], v[128:131], v[30:33], v[124:127]
	v_mfma_f32_16x16x32_bf16 v[188:191], v[128:131], v[22:25], v[188:191]
	s_setprio 0
	s_nop 0
	v_fma_f32 v124, v132, s96, -v215
	v_exp_f32_e32 v129, v124
	v_fma_f32 v124, v136, s96, -v215
	v_exp_f32_e32 v131, v124
	v_fma_f32 v124, v133, s96, -v215
	v_exp_f32_e32 v133, v124
	v_fma_f32 v124, v137, s96, -v215
	v_exp_f32_e32 v137, v124
	v_fma_f32 v124, v134, s96, -v215
	v_fma_f32 v134, v145, s96, -v216
	v_exp_f32_e32 v136, v134
	v_fma_f32 v134, v142, s96, -v216
	v_exp_f32_e32 v149, v124
	v_fma_f32 v124, v138, s96, -v215
	v_fma_f32 v128, v140, s96, -v216
	v_fma_f32 v132, v141, s96, -v216
	v_exp_f32_e32 v148, v134
	v_fma_f32 v134, v146, s96, -v216
	v_exp_f32_e32 v179, v124
	v_fma_f32 v124, v135, s96, -v215
	v_exp_f32_e32 v128, v128
	v_exp_f32_e32 v132, v132
	v_exp_f32_e32 v178, v134
	v_fma_f32 v134, v143, s96, -v216
	v_exp_f32_e32 v135, v124
	v_fma_f32 v124, v139, s96, -v215
	v_fma_f32 v130, v144, s96, -v216
	v_exp_f32_e32 v134, v134
	v_fma_f32 v138, v147, s96, -v216
	v_pk_add_f32 v[140:141], v[184:185], v[226:227]
	v_pk_add_f32 v[142:143], v[230:231], v[234:235]
	v_exp_f32_e32 v139, v124
	v_exp_f32_e32 v130, v130
	v_exp_f32_e32 v138, v138
	v_pk_add_f32 v[140:141], v[140:141], v[142:143]
	v_pk_add_f32 v[142:143], v[224:225], v[228:229]
	v_pk_add_f32 v[144:145], v[232:233], v[236:237]
	v_cvt_pk_bf16_f32 v124, v129, v133
	v_pk_add_f32 v[142:143], v[142:143], v[144:145]
	v_pk_add_f32 v[144:145], v[148:149], v[134:135]
	v_pk_add_f32 v[140:141], v[140:141], v[142:143]
	v_pk_add_f32 v[142:143], v[128:129], v[132:133]
	v_cvt_pk_bf16_f32 v128, v128, v132
	v_fma_f32 v132, v220, s96, -v217
	v_exp_f32_e32 v133, v132
	v_fma_f32 v132, v188, s96, -v217
	v_cvt_pk_bf16_f32 v125, v149, v135
	v_pk_add_f32 v[142:143], v[142:143], v[144:145]
	v_pk_add_f32 v[144:145], v[130:131], v[136:137]
	v_pk_add_f32 v[146:147], v[178:179], v[138:139]
	v_exp_f32_e32 v135, v132
	v_fma_f32 v132, v221, s96, -v217
	v_cvt_pk_bf16_f32 v126, v131, v137
	v_pk_add_f32 v[144:145], v[144:145], v[146:147]
	v_exp_f32_e32 v137, v132
	v_fma_f32 v132, v189, s96, -v217
	v_cvt_pk_bf16_f32 v127, v179, v139
	v_pk_add_f32 v[140:141], v[174:175], v[140:141]
	v_pk_add_f32 v[142:143], v[142:143], v[144:145]
	v_exp_f32_e32 v139, v132
	v_fma_f32 v132, v222, s96, -v217
	v_pk_add_f32 v[176:177], v[140:141], v[142:143]
	v_exp_f32_e32 v141, v132
	v_fma_f32 v132, v190, s96, -v217
	v_exp_f32_e32 v147, v132
	v_fma_f32 v132, v223, s96, -v217
	v_exp_f32_e32 v149, v132
	v_fma_f32 v132, v191, s96, -v217
	v_fma_f32 v106, v106, s96, -v218
	v_exp_f32_e32 v175, v132
	v_exp_f32_e32 v132, v106
	v_fma_f32 v106, v120, s96, -v218
	v_cvt_pk_bf16_f32 v129, v148, v134
	v_exp_f32_e32 v134, v106
	v_fma_f32 v106, v107, s96, -v218
	v_cvt_pk_bf16_f32 v130, v130, v136
	v_exp_f32_e32 v136, v106
	v_fma_f32 v106, v121, s96, -v218
	v_cvt_pk_bf16_f32 v131, v178, v138
	v_exp_f32_e32 v138, v106
	v_fma_f32 v106, v108, s96, -v218
	v_exp_f32_e32 v140, v106
	v_fma_f32 v106, v122, s96, -v218
	v_exp_f32_e32 v146, v106
	v_fma_f32 v106, v109, s96, -v218
	v_exp_f32_e32 v148, v106
	v_fma_f32 v106, v123, s96, -v218
	v_exp_f32_e32 v174, v106
	v_pk_add_f32 v[106:107], v[114:115], v[118:119]
	v_pk_add_f32 v[108:109], v[116:117], v[238:239]
	v_pk_add_f32 v[102:103], v[102:103], v[110:111]
	v_pk_add_f32 v[104:105], v[104:105], v[112:113]
	v_pk_add_f32 v[106:107], v[106:107], v[108:109]
	v_pk_add_f32 v[102:103], v[102:103], v[104:105]
	v_pk_add_f32 v[104:105], v[132:133], v[136:137]
	v_pk_add_f32 v[102:103], v[106:107], v[102:103]
	v_pk_add_f32 v[106:107], v[140:141], v[148:149]
	v_pk_add_f32 v[108:109], v[146:147], v[174:175]
	v_pk_add_f32 v[104:105], v[104:105], v[106:107]
	v_pk_add_f32 v[106:107], v[134:135], v[138:139]
	v_pk_add_f32 v[102:103], v[172:173], v[102:103]
	v_pk_add_f32 v[106:107], v[106:107], v[108:109]
	v_cvt_pk_bf16_f32 v142, v133, v137
	v_pk_add_f32 v[104:105], v[104:105], v[106:107]
	v_cvt_pk_bf16_f32 v143, v141, v149
	v_cvt_pk_bf16_f32 v144, v135, v139
	v_cvt_pk_bf16_f32 v145, v147, v175
	v_pk_add_f32 v[172:173], v[102:103], v[104:105]
	v_cvt_pk_bf16_f32 v106, v132, v136
	v_cvt_pk_bf16_f32 v107, v140, v148
	v_cvt_pk_bf16_f32 v108, v134, v138
	v_cvt_pk_bf16_f32 v109, v146, v174
	s_setprio 1
	s_waitcnt lgkmcnt(3)
	v_mfma_f32_16x16x32_bf16 v[86:89], v[98:101], v[124:127], v[86:89]
	s_waitcnt lgkmcnt(2)
	v_mfma_f32_16x16x32_bf16 v[94:97], v[150:153], v[124:127], v[94:97]
	s_waitcnt lgkmcnt(1)
	v_mfma_f32_16x16x32_bf16 v[90:93], v[154:157], v[124:127], v[90:93]
	s_waitcnt lgkmcnt(0)
	v_mfma_f32_16x16x32_bf16 v[82:85], v[158:161], v[124:127], v[82:85]
	v_mfma_f32_16x16x32_bf16 v[78:81], v[98:101], v[128:131], v[78:81]
	v_mfma_f32_16x16x32_bf16 v[74:77], v[150:153], v[128:131], v[74:77]
	v_mfma_f32_16x16x32_bf16 v[70:73], v[154:157], v[128:131], v[70:73]
	v_mfma_f32_16x16x32_bf16 v[66:69], v[158:161], v[128:131], v[66:69]
	v_mfma_f32_16x16x32_bf16 v[62:65], v[98:101], v[142:145], v[62:65]
	v_mfma_f32_16x16x32_bf16 v[58:61], v[150:153], v[142:145], v[58:61]
	v_mfma_f32_16x16x32_bf16 v[54:57], v[154:157], v[142:145], v[54:57]
	v_mfma_f32_16x16x32_bf16 v[50:53], v[158:161], v[142:145], v[50:53]
	v_mfma_f32_16x16x32_bf16 v[46:49], v[98:101], v[106:109], v[46:49]
	v_mfma_f32_16x16x32_bf16 v[42:45], v[150:153], v[106:109], v[42:45]
	v_mfma_f32_16x16x32_bf16 v[38:41], v[154:157], v[106:109], v[38:41]
	v_mfma_f32_16x16x32_bf16 v[34:37], v[158:161], v[106:109], v[34:37]
	s_setprio 0
	s_nop 7
	s_nop 1
	v_mov_b32_e32 v106, v86
	v_mov_b32_e32 v107, v87
	v_mov_b32_e32 v108, v88
	v_mov_b32_e32 v109, v89
	v_mov_b32_e32 v98, v94
	v_mov_b32_e32 v99, v95
	v_mov_b32_e32 v100, v96
	v_mov_b32_e32 v101, v97
	v_mov_b32_e32 v174, v176
	v_mov_b32_e32 v175, v177
; #define AT_WAIT_BAR(N) asm volatile("s_waitcnt vmcnt(" #N ") lgkmcnt(0)\n\ts_barrier" ::: "memory")
; DI void attn_even_lds(Frame& F, const float* rpb  , const float* gk  , const float* gq  ) {
;     ...
;         for (int s = 0; s < n; ++s) {
;             if (s + 2 < n) AT_WAIT_BAR(4); else if (s + 1 < n) AT_WAIT_BAR(2); else AT_WAIT_BAR(0);
;             if (s + 3 < n) AT_ISSUE(s + 3);
;     ...
;         { int ln_ = F.lane; asm volatile("" : "+v"(ln_));
;           bf16_t* op = MIX + (size_t)(b * SEQ + r * 64 + (ln_ & 15)) * DM + h * 64 + 4 * (ln_ >> 4);
; #pragma unroll
;           for (int j = 0; j < 4; ++j) attn_store(op + (size_t)(16 * j) * DM, o[j], ls[j]); }
.LBB0_319:
	s_addk_i32 s36, 0x7c
	s_add_u32 s4, s4, 1
	s_addc_u32 s5, s5, 0
	s_add_i32 s12, s77, s4
	s_add_i32 s20, s20, 64
	s_cmp_eq_u32 s12, 5
	s_cbranch_scc0 .LBB0_299
	s_nop 7
	s_nop 1
	v_mov_b32_e32 v86, v106
	v_mov_b32_e32 v87, v107
	v_mov_b32_e32 v88, v108
	v_mov_b32_e32 v89, v109
	v_mov_b32_e32 v94, v98
	v_mov_b32_e32 v95, v99
	v_mov_b32_e32 v96, v100
	v_mov_b32_e32 v97, v101
	v_mov_b32_e32 v102, v90
	v_mov_b32_e32 v103, v91
	v_mov_b32_e32 v104, v92
	v_mov_b32_e32 v105, v93
	v_mov_b32_e32 v110, v82
	v_mov_b32_e32 v111, v83
	v_mov_b32_e32 v112, v84
	v_mov_b32_e32 v113, v85
	v_mov_b32_e32 v114, v78
	v_mov_b32_e32 v115, v79
	v_mov_b32_e32 v116, v80
	v_mov_b32_e32 v117, v81
	v_mov_b32_e32 v118, v74
	v_mov_b32_e32 v119, v75
	v_mov_b32_e32 v120, v76
	v_mov_b32_e32 v121, v77
	v_mov_b32_e32 v122, v70
	v_mov_b32_e32 v123, v71
	v_mov_b32_e32 v124, v72
	v_mov_b32_e32 v125, v73
	v_mov_b32_e32 v126, v66
	v_mov_b32_e32 v127, v67
	v_mov_b32_e32 v128, v68
	v_mov_b32_e32 v129, v69
	v_mov_b32_e32 v130, v62
	v_mov_b32_e32 v131, v63
	v_mov_b32_e32 v132, v64
	v_mov_b32_e32 v133, v65
	v_mov_b32_e32 v134, v58
	v_mov_b32_e32 v135, v59
	v_mov_b32_e32 v136, v60
	v_mov_b32_e32 v137, v61
	v_mov_b32_e32 v138, v54
	v_mov_b32_e32 v139, v55
	v_mov_b32_e32 v140, v56
	v_mov_b32_e32 v141, v57
	v_mov_b32_e32 v142, v50
	v_mov_b32_e32 v143, v51
	v_mov_b32_e32 v144, v52
	v_mov_b32_e32 v145, v53
	v_mov_b32_e32 v146, v46
	v_mov_b32_e32 v147, v47
	v_mov_b32_e32 v148, v48
	v_mov_b32_e32 v149, v49
	v_mov_b32_e32 v150, v42
	v_mov_b32_e32 v151, v43
	v_mov_b32_e32 v152, v44
	v_mov_b32_e32 v153, v45
	v_mov_b32_e32 v154, v38
	v_mov_b32_e32 v155, v39
	v_mov_b32_e32 v156, v40
	v_mov_b32_e32 v157, v41
	v_mov_b32_e32 v158, v34
	v_mov_b32_e32 v159, v35
	v_mov_b32_e32 v160, v36
	v_mov_b32_e32 v161, v37
	v_mov_b32_e32 v176, v174
	v_mov_b32_e32 v177, v175
	v_mov_b32_e32 v178, v172
	v_mov_b32_e32 v179, v173
	s_branch .LBB0_282
